# FFT twiddle reads hoisted to the top of each radix-4 stage; extra-pass compare no longer clobbers the loop-invariant vcc mask
# speedup vs baseline: 1.0464x; 1.0147x over previous
.LBB0_1393:
	s_sub_i32 s1, 0, s0
	v_and_b32_e32 v184, s1, v32
	ds_read2st64_b64 v[0:3], v145 offset1:8
	ds_read2st64_b64 v[4:7], v145 offset0:32 offset1:40
	ds_read2st64_b64 v[16:19], v145 offset0:64 offset1:72
	ds_read2st64_b64 v[20:23], v145 offset0:96 offset1:104
	ds_read_b64 v[126:127], v33
	ds_read_b64 v[130:131], v146
	ds_read_b64 v[112:113], v148
	ds_read_b64 v[116:117], v149
	ds_read_b64 v[136:137], v156
	ds_read_b64 v[138:139], v157
	ds_read_b64 v[118:119], v158
	ds_read_b64 v[122:123], v159
	ds_read2st64_b64 v[8:11], v145 offset0:16 offset1:24
	ds_read2st64_b64 v[12:15], v145 offset0:48 offset1:56
	ds_read2st64_b64 v[24:27], v145 offset0:80 offset1:88
	ds_read2st64_b64 v[28:31], v145 offset0:112 offset1:120
	ds_read_b64 v[132:133], v151
	ds_read_b64 v[134:135], v152
	ds_read_b64 v[114:115], v154
	ds_read_b64 v[120:121], v155
	ds_read_b64 v[140:141], v160
	ds_read_b64 v[142:143], v161
	ds_read_b64 v[124:125], v162
	ds_read_b64 v[128:129], v163
	v_and_b32_e32 v185, s1, v147
	v_lshl_add_u32 v184, v184, 3, s29
	s_waitcnt lgkmcnt(0)
	s_barrier
	v_lshl_add_u32 v196, v185, 3, s29
	ds_read_b64 v[184:185], v184
	v_and_b32_e32 v186, s1, v150
	v_and_b32_e32 v187, s1, v153
	v_lshl_add_u32 v197, v186, 3, s29
	v_lshl_add_u32 v198, v187, 3, s29
	ds_read_b64 v[200:201], v196
	ds_read_b64 v[202:203], v197
	ds_read_b64 v[204:205], v198
	v_pk_add_f32 v[186:187], v[0:1], v[16:17]
	v_pk_add_f32 v[188:189], v[0:1], v[16:17] neg_lo:[0,1] neg_hi:[0,1]
	v_pk_add_f32 v[0:1], v[4:5], v[20:21]
	v_pk_add_f32 v[4:5], v[4:5], v[20:21] neg_lo:[0,1] neg_hi:[0,1]
	v_pk_add_f32 v[16:17], v[126:127], v[130:131]
	v_pk_add_f32 v[126:127], v[126:127], v[130:131] neg_lo:[0,1] neg_hi:[0,1]
	v_pk_add_f32 v[20:21], v[136:137], v[138:139]
	v_pk_add_f32 v[130:131], v[136:137], v[138:139] neg_lo:[0,1] neg_hi:[0,1]
	v_pk_add_f32 v[136:137], v[2:3], v[18:19]
	v_pk_add_f32 v[2:3], v[2:3], v[18:19] neg_lo:[0,1] neg_hi:[0,1]
	v_pk_add_f32 v[18:19], v[6:7], v[22:23]
	v_pk_add_f32 v[6:7], v[6:7], v[22:23] neg_lo:[0,1] neg_hi:[0,1]
	v_pk_add_f32 v[22:23], v[112:113], v[116:117]
	v_pk_add_f32 v[112:113], v[112:113], v[116:117] neg_lo:[0,1] neg_hi:[0,1]
	v_pk_add_f32 v[116:117], v[118:119], v[122:123]
	v_pk_add_f32 v[118:119], v[118:119], v[122:123] neg_lo:[0,1] neg_hi:[0,1]
	v_pk_add_f32 v[122:123], v[8:9], v[24:25]
	v_pk_add_f32 v[138:139], v[8:9], v[24:25] neg_lo:[0,1] neg_hi:[0,1]
	v_pk_add_f32 v[24:25], v[12:13], v[28:29]
	v_pk_add_f32 v[28:29], v[12:13], v[28:29] neg_lo:[0,1] neg_hi:[0,1]
	v_pk_add_f32 v[190:191], v[132:133], v[134:135]
	v_pk_add_f32 v[132:133], v[132:133], v[134:135] neg_lo:[0,1] neg_hi:[0,1]
	v_pk_add_f32 v[134:135], v[140:141], v[142:143]
	v_pk_add_f32 v[140:141], v[140:141], v[142:143] neg_lo:[0,1] neg_hi:[0,1]
	v_pk_add_f32 v[142:143], v[10:11], v[26:27]
	v_pk_add_f32 v[10:11], v[10:11], v[26:27] neg_lo:[0,1] neg_hi:[0,1]
	v_pk_add_f32 v[26:27], v[14:15], v[30:31]
	v_pk_add_f32 v[14:15], v[14:15], v[30:31] neg_lo:[0,1] neg_hi:[0,1]
	v_pk_add_f32 v[30:31], v[114:115], v[120:121]
	v_pk_add_f32 v[114:115], v[114:115], v[120:121] neg_lo:[0,1] neg_hi:[0,1]
	v_pk_add_f32 v[120:121], v[124:125], v[128:129]
	v_pk_add_f32 v[124:125], v[124:125], v[128:129] neg_lo:[0,1] neg_hi:[0,1]
	v_pk_mul_f32 v[128:129], v[4:5], s[58:59]
	v_pk_add_f32 v[192:193], v[186:187], v[0:1] neg_lo:[0,1] neg_hi:[0,1]
	v_pk_add_f32 v[0:1], v[186:187], v[0:1]
	v_pk_add_f32 v[186:187], v[16:17], v[20:21] neg_lo:[0,1] neg_hi:[0,1]
	v_pk_add_f32 v[4:5], v[16:17], v[20:21]
	v_pk_add_f32 v[194:195], v[136:137], v[18:19] neg_lo:[0,1] neg_hi:[0,1]
	v_pk_add_f32 v[8:9], v[136:137], v[18:19]
	v_pk_mul_f32 v[18:19], v[118:119], s[58:59]
	v_pk_add_f32 v[118:119], v[22:23], v[116:117] neg_lo:[0,1] neg_hi:[0,1]
	v_pk_add_f32 v[12:13], v[22:23], v[116:117]
	v_pk_mul_f32 v[22:23], v[28:29], s[58:59]
	v_pk_add_f32 v[116:117], v[122:123], v[24:25] neg_lo:[0,1] neg_hi:[0,1]
	v_pk_add_f32 v[16:17], v[122:123], v[24:25]
	v_pk_mul_f32 v[122:123], v[140:141], s[58:59]
	v_pk_mul_f32 v[14:15], v[14:15], s[58:59]
	v_pk_mul_f32 v[130:131], v[130:131], s[58:59]
	v_pk_mul_f32 v[6:7], v[6:7], s[58:59]
	v_pk_add_f32 v[136:137], v[190:191], v[134:135] neg_lo:[0,1] neg_hi:[0,1]
	v_pk_add_f32 v[20:21], v[190:191], v[134:135]
	v_pk_add_f32 v[134:135], v[142:143], v[26:27] neg_lo:[0,1] neg_hi:[0,1]
	v_pk_add_f32 v[24:25], v[142:143], v[26:27]
	v_pk_mul_f32 v[26:27], v[124:125], s[58:59]
	v_pk_add_f32 v[124:125], v[30:31], v[120:121] neg_lo:[0,1] neg_hi:[0,1]
	v_pk_add_f32 v[28:29], v[30:31], v[120:121]
	v_pk_add_f32 v[30:31], v[188:189], v[128:129] op_sel:[0,1] op_sel_hi:[1,0]
	v_pk_add_f32 v[120:121], v[188:189], v[128:129] op_sel:[0,1] op_sel_hi:[1,0] neg_lo:[0,1] neg_hi:[0,1]
	v_pk_add_f32 v[142:143], v[112:113], v[18:19] op_sel:[0,1] op_sel_hi:[1,0]
	v_pk_add_f32 v[18:19], v[112:113], v[18:19] op_sel:[0,1] op_sel_hi:[1,0] neg_lo:[0,1] neg_hi:[0,1]
	v_pk_add_f32 v[112:113], v[138:139], v[22:23] op_sel:[0,1] op_sel_hi:[1,0]
	v_pk_add_f32 v[138:139], v[138:139], v[22:23] op_sel:[0,1] op_sel_hi:[1,0] neg_lo:[0,1] neg_hi:[0,1]
	v_pk_add_f32 v[22:23], v[132:133], v[122:123] op_sel:[0,1] op_sel_hi:[1,0]
	v_pk_add_f32 v[122:123], v[132:133], v[122:123] op_sel:[0,1] op_sel_hi:[1,0] neg_lo:[0,1] neg_hi:[0,1]
	v_pk_add_f32 v[132:133], v[10:11], v[14:15] op_sel:[0,1] op_sel_hi:[1,0]
	v_pk_add_f32 v[188:189], v[10:11], v[14:15] op_sel:[0,1] op_sel_hi:[1,0] neg_lo:[0,1] neg_hi:[0,1]
	s_waitcnt lgkmcnt(0)
	v_xor_b32_e32 v10, 0x80000000, v185
	v_mov_b32_e32 v11, v185
	v_pk_add_f32 v[128:129], v[126:127], v[130:131] op_sel:[0,1] op_sel_hi:[1,0]
	v_pk_add_f32 v[126:127], v[126:127], v[130:131] op_sel:[0,1] op_sel_hi:[1,0] neg_lo:[0,1] neg_hi:[0,1]
	v_pk_add_f32 v[130:131], v[2:3], v[6:7] op_sel:[0,1] op_sel_hi:[1,0]
	v_pk_add_f32 v[140:141], v[2:3], v[6:7] op_sel:[0,1] op_sel_hi:[1,0] neg_lo:[0,1] neg_hi:[0,1]
	v_pk_mul_f32 v[2:3], v[184:185], v[10:11] op_sel:[1,0] op_sel_hi:[0,1]
	v_pk_add_f32 v[190:191], v[114:115], v[26:27] op_sel:[0,1] op_sel_hi:[1,0]
	v_pk_add_f32 v[114:115], v[114:115], v[26:27] op_sel:[0,1] op_sel_hi:[1,0] neg_lo:[0,1] neg_hi:[0,1]
	v_pk_mul_f32 v[6:7], v[10:11], v[30:31] op_sel:[0,1] op_sel_hi:[1,0]
	v_pk_mul_f32 v[14:15], v[10:11], v[128:129] op_sel:[0,1] op_sel_hi:[1,0]
	v_pk_fma_f32 v[26:27], v[184:185], v[184:185], v[2:3] op_sel_hi:[1,0,1]
	v_pk_fma_f32 v[2:3], v[184:185], v[30:31], v[6:7] op_sel_hi:[0,1,1]
	v_pk_fma_f32 v[6:7], v[184:185], v[128:129], v[14:15] op_sel_hi:[0,1,1]
	v_pk_mul_f32 v[10:11], v[10:11], v[26:27] op_sel:[0,1] op_sel_hi:[1,0]
	v_xor_b32_e32 v14, 0x80000000, v27
	v_mov_b32_e32 v15, v27
	ds_write_b128 v180, v[0:3]
	ds_write_b128 v164, v[4:7]
	v_pk_fma_f32 v[6:7], v[184:185], v[26:27], v[10:11] op_sel_hi:[0,1,1]
	v_pk_mul_f32 v[2:3], v[14:15], v[186:187] op_sel:[0,1] op_sel_hi:[1,0]
	v_xor_b32_e32 v10, 0x80000000, v7
	v_mov_b32_e32 v11, v7
	v_pk_mul_f32 v[0:1], v[14:15], v[192:193] op_sel:[0,1] op_sel_hi:[1,0]
	v_pk_fma_f32 v[4:5], v[26:27], v[186:187], v[2:3] op_sel_hi:[0,1,1]
	v_pk_mul_f32 v[2:3], v[120:121], v[10:11] op_sel:[1,0] op_sel_hi:[0,1]
	v_pk_fma_f32 v[0:1], v[26:27], v[192:193], v[0:1] op_sel_hi:[0,1,1]
	v_pk_mul_f32 v[10:11], v[10:11], v[126:127] op_sel:[0,1] op_sel_hi:[1,0]
	v_pk_fma_f32 v[2:3], v[120:121], v[6:7], v[2:3] op_sel_hi:[1,0,1]
	v_pk_fma_f32 v[6:7], v[6:7], v[126:127], v[10:11] op_sel_hi:[0,1,1]
	ds_write_b128 v180, v[0:3] offset:16
	ds_write_b128 v164, v[4:7] offset:16
	v_mov_b64_e32 v[0:1], v[200:201]
	s_lshl_b32 s0, s0, 2
	s_cmpk_gt_i32 s0, 0x400
	v_xor_b32_e32 v2, 0x80000000, v1
	v_mov_b32_e32 v3, v1
	v_pk_mul_f32 v[4:5], v[0:1], v[2:3] op_sel:[1,0] op_sel_hi:[0,1]
	v_pk_mul_f32 v[6:7], v[2:3], v[130:131] op_sel:[0,1] op_sel_hi:[1,0]
	v_pk_fma_f32 v[4:5], v[0:1], v[0:1], v[4:5] op_sel_hi:[1,0,1]
	v_pk_mul_f32 v[14:15], v[2:3], v[142:143] op_sel:[0,1] op_sel_hi:[1,0]
	v_pk_fma_f32 v[10:11], v[0:1], v[130:131], v[6:7] op_sel_hi:[0,1,1]
	v_pk_mul_f32 v[2:3], v[2:3], v[4:5] op_sel:[0,1] op_sel_hi:[1,0]
	v_pk_fma_f32 v[14:15], v[0:1], v[142:143], v[14:15] op_sel_hi:[0,1,1]
	v_xor_b32_e32 v6, 0x80000000, v5
	v_mov_b32_e32 v7, v5
	ds_write_b128 v165, v[8:11]
	ds_write_b128 v166, v[12:15]
	v_pk_fma_f32 v[8:9], v[0:1], v[4:5], v[2:3] op_sel_hi:[0,1,1]
	v_pk_mul_f32 v[0:1], v[6:7], v[194:195] op_sel:[0,1] op_sel_hi:[1,0]
	v_pk_mul_f32 v[2:3], v[6:7], v[118:119] op_sel:[0,1] op_sel_hi:[1,0]
	v_xor_b32_e32 v6, 0x80000000, v9
	v_mov_b32_e32 v7, v9
	v_pk_fma_f32 v[0:1], v[4:5], v[194:195], v[0:1] op_sel_hi:[0,1,1]
	v_pk_fma_f32 v[4:5], v[4:5], v[118:119], v[2:3] op_sel_hi:[0,1,1]
	v_pk_mul_f32 v[2:3], v[140:141], v[6:7] op_sel:[1,0] op_sel_hi:[0,1]
	v_pk_mul_f32 v[6:7], v[6:7], v[18:19] op_sel:[0,1] op_sel_hi:[1,0]
	v_pk_fma_f32 v[2:3], v[140:141], v[8:9], v[2:3] op_sel_hi:[1,0,1]
	v_pk_fma_f32 v[6:7], v[8:9], v[18:19], v[6:7] op_sel_hi:[0,1,1]
	ds_write_b128 v165, v[0:3] offset:16
	ds_write_b128 v166, v[4:7] offset:16
	v_mov_b64_e32 v[0:1], v[202:203]
	v_xor_b32_e32 v2, 0x80000000, v1
	v_mov_b32_e32 v3, v1
	v_pk_mul_f32 v[4:5], v[0:1], v[2:3] op_sel:[1,0] op_sel_hi:[0,1]
	v_pk_fma_f32 v[4:5], v[0:1], v[0:1], v[4:5] op_sel_hi:[1,0,1]
	v_pk_mul_f32 v[6:7], v[2:3], v[112:113] op_sel:[0,1] op_sel_hi:[1,0]
	v_pk_mul_f32 v[8:9], v[2:3], v[22:23] op_sel:[0,1] op_sel_hi:[1,0]
	v_pk_mul_f32 v[2:3], v[2:3], v[4:5] op_sel:[0,1] op_sel_hi:[1,0]
	v_pk_fma_f32 v[18:19], v[0:1], v[112:113], v[6:7] op_sel_hi:[0,1,1]
	v_pk_fma_f32 v[22:23], v[0:1], v[22:23], v[8:9] op_sel_hi:[0,1,1]
	v_xor_b32_e32 v6, 0x80000000, v5
	v_mov_b32_e32 v7, v5
	v_pk_fma_f32 v[8:9], v[0:1], v[4:5], v[2:3] op_sel_hi:[0,1,1]
	v_pk_mul_f32 v[0:1], v[6:7], v[116:117] op_sel:[0,1] op_sel_hi:[1,0]
	v_pk_mul_f32 v[2:3], v[6:7], v[136:137] op_sel:[0,1] op_sel_hi:[1,0]
	v_xor_b32_e32 v6, 0x80000000, v9
	v_mov_b32_e32 v7, v9
	v_pk_fma_f32 v[0:1], v[4:5], v[116:117], v[0:1] op_sel_hi:[0,1,1]
	v_pk_fma_f32 v[4:5], v[4:5], v[136:137], v[2:3] op_sel_hi:[0,1,1]
	v_pk_mul_f32 v[2:3], v[138:139], v[6:7] op_sel:[1,0] op_sel_hi:[0,1]
	v_pk_mul_f32 v[6:7], v[6:7], v[122:123] op_sel:[0,1] op_sel_hi:[1,0]
	v_pk_fma_f32 v[2:3], v[138:139], v[8:9], v[2:3] op_sel_hi:[1,0,1]
	ds_write_b128 v167, v[16:19]
	ds_write_b128 v168, v[20:23]
	v_pk_fma_f32 v[6:7], v[8:9], v[122:123], v[6:7] op_sel_hi:[0,1,1]
	ds_write_b128 v167, v[0:3] offset:16
	ds_write_b128 v168, v[4:7] offset:16
	v_mov_b64_e32 v[0:1], v[204:205]
	v_xor_b32_e32 v2, 0x80000000, v1
	v_mov_b32_e32 v3, v1
	v_pk_mul_f32 v[4:5], v[0:1], v[2:3] op_sel:[1,0] op_sel_hi:[0,1]
	v_pk_fma_f32 v[4:5], v[0:1], v[0:1], v[4:5] op_sel_hi:[1,0,1]
	v_pk_mul_f32 v[6:7], v[2:3], v[132:133] op_sel:[0,1] op_sel_hi:[1,0]
	v_pk_mul_f32 v[8:9], v[2:3], v[190:191] op_sel:[0,1] op_sel_hi:[1,0]
	v_pk_mul_f32 v[2:3], v[2:3], v[4:5] op_sel:[0,1] op_sel_hi:[1,0]
	v_pk_fma_f32 v[26:27], v[0:1], v[132:133], v[6:7] op_sel_hi:[0,1,1]
	v_pk_fma_f32 v[30:31], v[0:1], v[190:191], v[8:9] op_sel_hi:[0,1,1]
	v_xor_b32_e32 v6, 0x80000000, v5
	v_mov_b32_e32 v7, v5
	v_pk_fma_f32 v[8:9], v[0:1], v[4:5], v[2:3] op_sel_hi:[0,1,1]
	v_pk_mul_f32 v[0:1], v[6:7], v[134:135] op_sel:[0,1] op_sel_hi:[1,0]
	v_pk_mul_f32 v[2:3], v[6:7], v[124:125] op_sel:[0,1] op_sel_hi:[1,0]
	v_xor_b32_e32 v6, 0x80000000, v9
	v_mov_b32_e32 v7, v9
	v_pk_fma_f32 v[0:1], v[4:5], v[134:135], v[0:1] op_sel_hi:[0,1,1]
	v_pk_fma_f32 v[4:5], v[4:5], v[124:125], v[2:3] op_sel_hi:[0,1,1]
	v_pk_mul_f32 v[2:3], v[188:189], v[6:7] op_sel:[1,0] op_sel_hi:[0,1]
	v_pk_mul_f32 v[6:7], v[6:7], v[114:115] op_sel:[0,1] op_sel_hi:[1,0]
	v_pk_fma_f32 v[2:3], v[188:189], v[8:9], v[2:3] op_sel_hi:[1,0,1]
	ds_write_b128 v169, v[24:27]
	ds_write_b128 v170, v[28:31]
	v_pk_fma_f32 v[6:7], v[8:9], v[114:115], v[6:7] op_sel_hi:[0,1,1]
	ds_write_b128 v169, v[0:3] offset:16
	ds_write_b128 v170, v[4:7] offset:16
	s_waitcnt lgkmcnt(0)
	s_barrier
	s_cbranch_scc0 .LBB0_1393
	ds_read2st64_b64 v[0:3], v145 offset1:8
	ds_read2st64_b64 v[4:7], v145 offset0:64 offset1:72
	ds_read_b64 v[118:119], v33
	ds_read_b64 v[120:121], v146
	ds_read_b64 v[122:123], v148
	ds_read_b64 v[124:125], v149
	ds_read2st64_b64 v[8:11], v145 offset0:16 offset1:24
	ds_read2st64_b64 v[12:15], v145 offset0:80 offset1:88
	ds_read_b64 v[126:127], v151
	ds_read_b64 v[128:129], v152
	ds_read_b64 v[130:131], v154
	ds_read_b64 v[132:133], v155
	ds_read2st64_b64 v[16:19], v145 offset0:32 offset1:40
	ds_read2st64_b64 v[20:23], v145 offset0:96 offset1:104
	ds_read_b64 v[134:135], v156
	ds_read_b64 v[136:137], v157
	ds_read_b64 v[138:139], v158
	ds_read_b64 v[140:141], v159
	ds_read2st64_b64 v[24:27], v145 offset0:48 offset1:56
	ds_read2st64_b64 v[28:31], v145 offset0:112 offset1:120
	ds_read_b64 v[142:143], v160
	ds_read_b64 v[184:185], v161
	ds_read_b64 v[186:187], v162
	ds_read_b64 v[188:189], v163
	s_waitcnt lgkmcnt(14)
	v_pk_add_f32 v[112:113], v[0:1], v[4:5]
	v_pk_add_f32 v[114:115], v[0:1], v[4:5] neg_lo:[0,1] neg_hi:[0,1]
	v_pk_add_f32 v[0:1], v[2:3], v[6:7]
	v_pk_add_f32 v[2:3], v[2:3], v[6:7] neg_lo:[0,1] neg_hi:[0,1]
	s_waitcnt lgkmcnt(0)
	s_barrier
	v_pk_add_f32 v[116:117], v[118:119], v[120:121]
	v_pk_add_f32 v[118:119], v[118:119], v[120:121] neg_lo:[0,1] neg_hi:[0,1]
	ds_write_b128 v171, v[112:115]
	ds_write_b128 v172, v[116:119]
	v_pk_add_f32 v[4:5], v[122:123], v[124:125]
	v_pk_add_f32 v[6:7], v[122:123], v[124:125] neg_lo:[0,1] neg_hi:[0,1]
	ds_write_b128 v171, v[0:3] offset:8192
	ds_write_b128 v173, v[4:7]
	v_pk_add_f32 v[0:1], v[8:9], v[12:13]
	v_pk_add_f32 v[2:3], v[8:9], v[12:13] neg_lo:[0,1] neg_hi:[0,1]
	v_pk_add_f32 v[4:5], v[126:127], v[128:129]
	v_pk_add_f32 v[6:7], v[126:127], v[128:129] neg_lo:[0,1] neg_hi:[0,1]
	ds_write_b128 v171, v[0:3] offset:16384
	ds_write_b128 v174, v[4:7]
	v_pk_add_f32 v[0:1], v[10:11], v[14:15]
	v_pk_add_f32 v[2:3], v[10:11], v[14:15] neg_lo:[0,1] neg_hi:[0,1]
	v_pk_add_f32 v[4:5], v[130:131], v[132:133]
	v_pk_add_f32 v[6:7], v[130:131], v[132:133] neg_lo:[0,1] neg_hi:[0,1]
	ds_write_b128 v171, v[0:3] offset:24576
	ds_write_b128 v175, v[4:7]
	v_pk_add_f32 v[0:1], v[16:17], v[20:21]
	v_pk_add_f32 v[2:3], v[16:17], v[20:21] neg_lo:[0,1] neg_hi:[0,1]
	v_pk_add_f32 v[4:5], v[134:135], v[136:137]
	v_pk_add_f32 v[6:7], v[134:135], v[136:137] neg_lo:[0,1] neg_hi:[0,1]
	ds_write_b128 v171, v[0:3] offset:32768
	ds_write_b128 v176, v[4:7]
	v_pk_add_f32 v[0:1], v[18:19], v[22:23]
	v_pk_add_f32 v[2:3], v[18:19], v[22:23] neg_lo:[0,1] neg_hi:[0,1]
	v_pk_add_f32 v[4:5], v[138:139], v[140:141]
	v_pk_add_f32 v[6:7], v[138:139], v[140:141] neg_lo:[0,1] neg_hi:[0,1]
	ds_write_b128 v171, v[0:3] offset:40960
	ds_write_b128 v177, v[4:7]
	v_pk_add_f32 v[0:1], v[24:25], v[28:29]
	v_pk_add_f32 v[2:3], v[24:25], v[28:29] neg_lo:[0,1] neg_hi:[0,1]
	v_pk_add_f32 v[4:5], v[142:143], v[184:185]
	v_pk_add_f32 v[6:7], v[142:143], v[184:185] neg_lo:[0,1] neg_hi:[0,1]
	ds_write_b128 v171, v[0:3] offset:49152
	ds_write_b128 v178, v[4:7]
	v_pk_add_f32 v[0:1], v[26:27], v[30:31]
	v_pk_add_f32 v[2:3], v[26:27], v[30:31] neg_lo:[0,1] neg_hi:[0,1]
	v_pk_add_f32 v[4:5], v[186:187], v[188:189]
	v_pk_add_f32 v[6:7], v[186:187], v[188:189] neg_lo:[0,1] neg_hi:[0,1]
	ds_write_b128 v171, v[0:3] offset:57344
	ds_write_b128 v179, v[4:7]
	v_and_b32_e32 v2, 0xff, v32
	v_lshrrev_b32_e32 v0, 8, v32
	v_lshlrev_b32_e32 v2, 1, v2
	v_lshl_or_b32 v2, v0, 12, v2
	s_waitcnt lgkmcnt(0)
	s_barrier
	s_mov_b32 s40, 0
	v_lshlrev_b32_e32 v3, 5, v2
	v_lshlrev_b32_e32 v4, 9, v2
	v_lshlrev_b32_e32 v5, 12, v2
	v_lshrrev_b32_e32 v0, 3, v2
	v_lshlrev_b32_e32 v1, 1, v2
	v_and_b32_e32 v3, 0x300, v3
	v_and_b32_e32 v4, 0xc00, v4
	v_and_b32_e32 v5, 0x1000, v5
	v_and_b32_e32 v0, 48, v0
	v_and_b32_e32 v1, 0xc0, v1
	v_or3_b32 v3, v4, v5, v3
	v_or3_b32 v3, v3, v1, v0
	v_lshl_add_u32 v4, v2, 3, 0
	s_branch .LBB0_1396

.Lfft_k4096:
	s_mov_b32 s40, 0x20000
	v_cmp_eq_u32_e64 s[20:21], 0, v32
	s_nop 1
	v_cndmask_b32_e64 v2, 3, 1, s[20:21]
	v_lshlrev_b32_e32 v3, 5, v2
	v_lshlrev_b32_e32 v4, 9, v2
	v_lshlrev_b32_e32 v5, 12, v2
	v_lshrrev_b32_e32 v0, 3, v2
	v_lshlrev_b32_e32 v1, 1, v2
	v_and_b32_e32 v3, 0x300, v3
	v_and_b32_e32 v4, 0xc00, v4
	v_and_b32_e32 v5, 0x1000, v5
	v_and_b32_e32 v0, 48, v0
	v_and_b32_e32 v1, 0xc0, v1
	v_or3_b32 v3, v4, v5, v3
	v_or3_b32 v3, v3, v1, v0
	v_lshlrev_b32_e32 v4, 3, v2
	v_add_u32_e32 v4, 0xfffe0000, v4
	s_branch .LBB0_1396

.LBB0_1411:
	s_sub_i32 s1, 0, s0
	v_add_u32_e32 v96, 0, v144
	v_and_b32_e32 v128, s1, v32
	v_add_u32_e32 v124, 0x10000, v96
	v_and_b32_e32 v129, s1, v147
	v_lshl_add_u32 v128, v128, 3, s29
	ds_read_b128 v[96:99], v124
	ds_read_b128 v[100:103], v124 offset:16
	ds_read_b128 v[104:107], v124 offset:16384
	ds_read_b128 v[108:111], v124 offset:16400
	ds_read_b128 v[112:115], v124 offset:32768
	ds_read_b128 v[116:119], v124 offset:32784
	ds_read_b128 v[120:123], v124 offset:49152
	ds_read_b128 v[124:127], v124 offset:49168
	v_lshl_add_u32 v136, v129, 3, s29
	v_and_b32_e32 v130, s1, v150
	v_and_b32_e32 v131, s1, v153
	v_lshl_add_u32 v137, v130, 3, s29
	v_lshl_add_u32 v138, v131, 3, s29
	ds_read_b64 v[128:129], v128
	ds_read_b64 v[200:201], v136
	ds_read_b64 v[202:203], v137
	ds_read_b64 v[204:205], v138
	s_waitcnt lgkmcnt(0)
	s_barrier
	v_xor_b32_e32 v130, 0x80000000, v129
	v_mov_b32_e32 v131, v129
	v_mov_b32_e32 v132, v129
	v_pk_mul_f32 v[134:135], v[128:129], v[130:131] op_sel:[1,0] op_sel_hi:[0,1]
	v_mov_b32_e32 v133, v130
	v_pk_fma_f32 v[134:135], v[128:129], v[128:129], v[134:135] op_sel_hi:[1,0,1]
	v_pk_mul_f32 v[132:133], v[98:99], v[132:133] op_sel:[1,0] op_sel_hi:[0,1]
	v_pk_mul_f32 v[130:131], v[130:131], v[134:135] op_sel:[0,1] op_sel_hi:[1,0]
	v_pk_fma_f32 v[98:99], v[128:129], v[98:99], v[132:133] op_sel_hi:[0,1,1]
	v_pk_add_f32 v[132:133], v[134:135], 0 neg_lo:[1,1] neg_hi:[1,1]
	v_pk_fma_f32 v[128:129], v[128:129], v[134:135], v[130:131] op_sel_hi:[0,1,1]
	v_mov_b32_e32 v132, v135
	v_pk_mul_f32 v[130:131], v[100:101], v[132:133] op_sel:[1,0] op_sel_hi:[0,1]
	v_pk_add_f32 v[132:133], v[128:129], 0 neg_lo:[1,1] neg_hi:[1,1]
	v_pk_fma_f32 v[100:101], v[100:101], v[134:135], v[130:131] op_sel_hi:[1,0,1]
	v_mov_b32_e32 v132, v129
	v_pk_mul_f32 v[130:131], v[102:103], v[132:133] op_sel:[1,0] op_sel_hi:[0,1]
	v_pk_add_f32 v[132:133], v[96:97], v[100:101]
	v_pk_add_f32 v[96:97], v[96:97], v[100:101] neg_lo:[0,1] neg_hi:[0,1]
	v_pk_fma_f32 v[100:101], v[102:103], v[128:129], v[130:131] op_sel_hi:[1,0,1]
	s_lshr_b32 s4, s0, 2
	v_pk_add_f32 v[102:103], v[98:99], v[100:101]
	v_pk_add_f32 v[98:99], v[98:99], v[100:101] neg_lo:[0,1] neg_hi:[0,1]
	v_pk_add_f32 v[100:101], v[132:133], v[102:103]
	v_pk_mul_f32 v[98:99], v[98:99], s[58:59]
	v_pk_add_f32 v[102:103], v[132:133], v[102:103] neg_lo:[0,1] neg_hi:[0,1]
	v_pk_add_f32 v[128:129], v[96:97], v[98:99] op_sel:[0,1] op_sel_hi:[1,0] neg_lo:[0,1] neg_hi:[0,1]
	v_pk_add_f32 v[96:97], v[96:97], v[98:99] op_sel:[0,1] op_sel_hi:[1,0]
	ds_write2st64_b64 v33, v[100:101], v[128:129] offset1:32
	ds_write2st64_b64 v33, v[102:103], v[96:97] offset0:64 offset1:96
	v_mov_b64_e32 v[96:97], v[200:201]
	s_cmp_lt_u32 s0, 4
	s_mov_b32 s0, s4
	v_xor_b32_e32 v98, 0x80000000, v97
	v_mov_b32_e32 v99, v97
	v_mov_b32_e32 v100, v97
	v_pk_mul_f32 v[102:103], v[96:97], v[98:99] op_sel:[1,0] op_sel_hi:[0,1]
	v_mov_b32_e32 v101, v98
	v_pk_fma_f32 v[102:103], v[96:97], v[96:97], v[102:103] op_sel_hi:[1,0,1]
	v_pk_mul_f32 v[100:101], v[106:107], v[100:101] op_sel:[1,0] op_sel_hi:[0,1]
	v_pk_mul_f32 v[98:99], v[98:99], v[102:103] op_sel:[0,1] op_sel_hi:[1,0]
	v_pk_fma_f32 v[100:101], v[96:97], v[106:107], v[100:101] op_sel_hi:[0,1,1]
	v_pk_add_f32 v[106:107], v[102:103], 0 neg_lo:[1,1] neg_hi:[1,1]
	v_pk_fma_f32 v[96:97], v[96:97], v[102:103], v[98:99] op_sel_hi:[0,1,1]
	v_mov_b32_e32 v106, v103
	v_pk_mul_f32 v[98:99], v[108:109], v[106:107] op_sel:[1,0] op_sel_hi:[0,1]
	v_pk_add_f32 v[106:107], v[96:97], 0 neg_lo:[1,1] neg_hi:[1,1]
	v_pk_fma_f32 v[98:99], v[108:109], v[102:103], v[98:99] op_sel_hi:[1,0,1]
	v_mov_b32_e32 v106, v97
	v_pk_mul_f32 v[102:103], v[110:111], v[106:107] op_sel:[1,0] op_sel_hi:[0,1]
	v_pk_fma_f32 v[96:97], v[110:111], v[96:97], v[102:103] op_sel_hi:[1,0,1]
	v_pk_add_f32 v[106:107], v[104:105], v[98:99]
	v_pk_add_f32 v[102:103], v[100:101], v[96:97]
	v_pk_add_f32 v[96:97], v[100:101], v[96:97] neg_lo:[0,1] neg_hi:[0,1]
	v_pk_add_f32 v[98:99], v[104:105], v[98:99] neg_lo:[0,1] neg_hi:[0,1]
	v_pk_mul_f32 v[96:97], v[96:97], s[58:59]
	v_pk_add_f32 v[100:101], v[106:107], v[102:103]
	v_pk_add_f32 v[104:105], v[98:99], v[96:97] op_sel:[0,1] op_sel_hi:[1,0] neg_lo:[0,1] neg_hi:[0,1]
	v_pk_add_f32 v[102:103], v[106:107], v[102:103] neg_lo:[0,1] neg_hi:[0,1]
	v_pk_add_f32 v[96:97], v[98:99], v[96:97] op_sel:[0,1] op_sel_hi:[1,0]
	ds_write2st64_b64 v148, v[100:101], v[104:105] offset1:32
	ds_write2st64_b64 v148, v[102:103], v[96:97] offset0:64 offset1:96
	v_mov_b64_e32 v[96:97], v[202:203]
	v_xor_b32_e32 v98, 0x80000000, v97
	v_mov_b32_e32 v99, v97
	v_pk_mul_f32 v[102:103], v[96:97], v[98:99] op_sel:[1,0] op_sel_hi:[0,1]
	v_mov_b32_e32 v100, v97
	v_mov_b32_e32 v101, v98
	v_pk_fma_f32 v[102:103], v[96:97], v[96:97], v[102:103] op_sel_hi:[1,0,1]
	v_pk_mul_f32 v[100:101], v[114:115], v[100:101] op_sel:[1,0] op_sel_hi:[0,1]
	v_pk_mul_f32 v[98:99], v[98:99], v[102:103] op_sel:[0,1] op_sel_hi:[1,0]
	v_pk_add_f32 v[104:105], v[102:103], 0 neg_lo:[1,1] neg_hi:[1,1]
	v_pk_fma_f32 v[100:101], v[96:97], v[114:115], v[100:101] op_sel_hi:[0,1,1]
	v_pk_fma_f32 v[96:97], v[96:97], v[102:103], v[98:99] op_sel_hi:[0,1,1]
	v_mov_b32_e32 v104, v103
	v_pk_mul_f32 v[98:99], v[116:117], v[104:105] op_sel:[1,0] op_sel_hi:[0,1]
	v_pk_add_f32 v[104:105], v[96:97], 0 neg_lo:[1,1] neg_hi:[1,1]
	v_pk_fma_f32 v[98:99], v[116:117], v[102:103], v[98:99] op_sel_hi:[1,0,1]
	v_mov_b32_e32 v104, v97
	v_pk_mul_f32 v[102:103], v[118:119], v[104:105] op_sel:[1,0] op_sel_hi:[0,1]
	v_pk_fma_f32 v[96:97], v[118:119], v[96:97], v[102:103] op_sel_hi:[1,0,1]
	v_pk_add_f32 v[104:105], v[112:113], v[98:99]
	v_pk_add_f32 v[102:103], v[100:101], v[96:97]
	v_pk_add_f32 v[96:97], v[100:101], v[96:97] neg_lo:[0,1] neg_hi:[0,1]
	v_pk_add_f32 v[98:99], v[112:113], v[98:99] neg_lo:[0,1] neg_hi:[0,1]
	v_pk_mul_f32 v[96:97], v[96:97], s[58:59]
	v_pk_add_f32 v[100:101], v[104:105], v[102:103]
	v_pk_add_f32 v[102:103], v[104:105], v[102:103] neg_lo:[0,1] neg_hi:[0,1]
	v_pk_add_f32 v[104:105], v[98:99], v[96:97] op_sel:[0,1] op_sel_hi:[1,0] neg_lo:[0,1] neg_hi:[0,1]
	v_pk_add_f32 v[96:97], v[98:99], v[96:97] op_sel:[0,1] op_sel_hi:[1,0]
	ds_write2st64_b64 v151, v[100:101], v[104:105] offset1:32
	ds_write2st64_b64 v151, v[102:103], v[96:97] offset0:64 offset1:96
	v_mov_b64_e32 v[96:97], v[204:205]
	v_xor_b32_e32 v98, 0x80000000, v97
	v_mov_b32_e32 v99, v97
	v_pk_mul_f32 v[102:103], v[96:97], v[98:99] op_sel:[1,0] op_sel_hi:[0,1]
	v_mov_b32_e32 v100, v97
	v_mov_b32_e32 v101, v98
	v_pk_fma_f32 v[102:103], v[96:97], v[96:97], v[102:103] op_sel_hi:[1,0,1]
	v_pk_mul_f32 v[100:101], v[122:123], v[100:101] op_sel:[1,0] op_sel_hi:[0,1]
	v_pk_mul_f32 v[98:99], v[98:99], v[102:103] op_sel:[0,1] op_sel_hi:[1,0]
	v_pk_add_f32 v[104:105], v[102:103], 0 neg_lo:[1,1] neg_hi:[1,1]
	v_pk_fma_f32 v[100:101], v[96:97], v[122:123], v[100:101] op_sel_hi:[0,1,1]
	v_pk_fma_f32 v[96:97], v[96:97], v[102:103], v[98:99] op_sel_hi:[0,1,1]
	v_mov_b32_e32 v104, v103
	v_pk_mul_f32 v[98:99], v[124:125], v[104:105] op_sel:[1,0] op_sel_hi:[0,1]
	v_pk_add_f32 v[104:105], v[96:97], 0 neg_lo:[1,1] neg_hi:[1,1]
	v_pk_fma_f32 v[98:99], v[124:125], v[102:103], v[98:99] op_sel_hi:[1,0,1]
	v_mov_b32_e32 v104, v97
	v_pk_mul_f32 v[102:103], v[126:127], v[104:105] op_sel:[1,0] op_sel_hi:[0,1]
	v_pk_fma_f32 v[96:97], v[126:127], v[96:97], v[102:103] op_sel_hi:[1,0,1]
	v_pk_add_f32 v[104:105], v[120:121], v[98:99]
	v_pk_add_f32 v[102:103], v[100:101], v[96:97]
	v_pk_add_f32 v[96:97], v[100:101], v[96:97] neg_lo:[0,1] neg_hi:[0,1]
	v_pk_add_f32 v[98:99], v[120:121], v[98:99] neg_lo:[0,1] neg_hi:[0,1]
	v_pk_mul_f32 v[96:97], v[96:97], s[58:59]
	v_pk_add_f32 v[100:101], v[104:105], v[102:103]
	v_pk_add_f32 v[102:103], v[104:105], v[102:103] neg_lo:[0,1] neg_hi:[0,1]
	v_pk_add_f32 v[104:105], v[98:99], v[96:97] op_sel:[0,1] op_sel_hi:[1,0] neg_lo:[0,1] neg_hi:[0,1]
	v_pk_add_f32 v[96:97], v[98:99], v[96:97] op_sel:[0,1] op_sel_hi:[1,0]
	ds_write2st64_b64 v154, v[100:101], v[104:105] offset1:32
	ds_write2st64_b64 v154, v[102:103], v[96:97] offset0:64 offset1:96
	s_waitcnt lgkmcnt(0)
	s_barrier
	s_cbranch_scc0 .LBB0_1411
	s_lshl_b64 s[0:1], s[68:69], 2
	s_add_u32 s0, s24, s0
	s_addc_u32 s1, s23, s1
	v_mov_b64_e32 v[96:97], s[0:1]
	flat_load_dword v96, v[96:97]
	ds_read_b64 v[98:99], v33
	ds_read_b64 v[100:101], v148
	ds_read_b64 v[102:103], v151
	ds_read_b64 v[104:105], v154
	ds_read_b64 v[106:107], v156
	ds_read_b64 v[108:109], v158
	ds_read_b64 v[110:111], v160
	ds_read_b64 v[112:113], v162
	s_add_u32 s0, s48, s20
	s_addc_u32 s1, s49, s21
	s_add_i32 s68, s68, s30
	v_lshl_add_u64 v[114:115], v[34:35], 2, s[0:1]
	s_cmpk_gt_i32 s68, 0x7ff
	v_lshl_add_u64 v[116:117], v[82:83], 2, s[0:1]
	v_lshl_add_u64 v[118:119], v[84:85], 2, s[0:1]
	v_lshl_add_u64 v[120:121], v[86:87], 2, s[0:1]
	v_lshl_add_u64 v[122:123], v[88:89], 2, s[0:1]
	v_lshl_add_u64 v[124:125], v[90:91], 2, s[0:1]
	v_lshl_add_u64 v[126:127], v[92:93], 2, s[0:1]
	v_lshl_add_u64 v[128:129], v[94:95], 2, s[0:1]
	s_waitcnt vmcnt(0) lgkmcnt(0)
	v_pk_mul_f32 v[8:9], v[96:97], v[8:9] op_sel_hi:[0,1]
	v_pk_mul_f32 v[10:11], v[96:97], v[10:11] op_sel_hi:[0,1]
	v_pk_mul_f32 v[12:13], v[96:97], v[12:13] op_sel_hi:[0,1]
	v_pk_mul_f32 v[14:15], v[96:97], v[14:15] op_sel_hi:[0,1]
	v_pk_mul_f32 v[24:25], v[96:97], v[24:25] op_sel_hi:[0,1]
	v_pk_mul_f32 v[26:27], v[96:97], v[26:27] op_sel_hi:[0,1]
	v_pk_mul_f32 v[28:29], v[96:97], v[28:29] op_sel_hi:[0,1]
	v_pk_mul_f32 v[30:31], v[96:97], v[30:31] op_sel_hi:[0,1]
	v_pk_fma_f32 v[8:9], v[98:99], s[66:67], v[8:9] op_sel_hi:[1,0,1]
	v_pk_fma_f32 v[10:11], v[100:101], s[66:67], v[10:11] op_sel_hi:[1,0,1]
	v_pk_fma_f32 v[12:13], v[102:103], s[66:67], v[12:13] op_sel_hi:[1,0,1]
	v_pk_fma_f32 v[14:15], v[104:105], s[66:67], v[14:15] op_sel_hi:[1,0,1]
	v_pk_fma_f32 v[24:25], v[106:107], s[66:67], v[24:25] op_sel_hi:[1,0,1]
	v_pk_fma_f32 v[26:27], v[108:109], s[66:67], v[26:27] op_sel_hi:[1,0,1]
	v_pk_fma_f32 v[28:29], v[110:111], s[66:67], v[28:29] op_sel_hi:[1,0,1]
	v_pk_fma_f32 v[30:31], v[112:113], s[66:67], v[30:31] op_sel_hi:[1,0,1]
	v_pk_mul_f32 v[0:1], v[0:1], v[8:9]
	v_pk_mul_f32 v[2:3], v[2:3], v[10:11]
	v_pk_mul_f32 v[4:5], v[4:5], v[12:13]
	v_pk_mul_f32 v[6:7], v[6:7], v[14:15]
	v_pk_mul_f32 v[8:9], v[16:17], v[24:25]
	v_pk_mul_f32 v[10:11], v[18:19], v[26:27]
	v_pk_mul_f32 v[12:13], v[20:21], v[28:29]
	v_pk_mul_f32 v[14:15], v[22:23], v[30:31]
	global_store_dwordx2 v[114:115], v[0:1], off
	global_store_dwordx2 v[116:117], v[2:3], off
	global_store_dwordx2 v[118:119], v[4:5], off
	global_store_dwordx2 v[120:121], v[6:7], off
	global_store_dwordx2 v[122:123], v[8:9], off
	global_store_dwordx2 v[124:125], v[10:11], off
	global_store_dwordx2 v[126:127], v[12:13], off
	global_store_dwordx2 v[128:129], v[14:15], off
	s_barrier
	s_cbranch_scc0 .LBB0_1376
